# idx top-k count: register groups that only hold slots beyond t are skipped (their count is known)
# speedup vs baseline: 1.0199x; 1.0199x over previous
.Lsel_row:
	s_or_b32 s27, s26, s4
	s_mul_i32 s0, s27, 0x2010
	v_add_u32_e32 v145, s0, v152
	s_add_i32 s27, s27, s33
	s_lshr_b32 s46, s27, 8
	s_add_i32 s46, s46, 1
	s_lshl_b32 s47, s46, 8
	s_sub_i32 s47, 0x800, s47
	ds_read2st64_b32 v[102:103], v145 offset0:0 offset1:1
	ds_read2st64_b32 v[104:105], v145 offset0:2 offset1:3
	ds_read2st64_b32 v[106:107], v145 offset0:4 offset1:5
	ds_read2st64_b32 v[108:109], v145 offset0:6 offset1:7
	ds_read2st64_b32 v[110:111], v145 offset0:8 offset1:9
	ds_read2st64_b32 v[112:113], v145 offset0:10 offset1:11
	ds_read2st64_b32 v[114:115], v145 offset0:12 offset1:13
	ds_read2st64_b32 v[116:117], v145 offset0:14 offset1:15
	ds_read2st64_b32 v[118:119], v145 offset0:16 offset1:17
	ds_read2st64_b32 v[120:121], v145 offset0:18 offset1:19
	ds_read2st64_b32 v[122:123], v145 offset0:20 offset1:21
	ds_read2st64_b32 v[124:125], v145 offset0:22 offset1:23
	ds_read2st64_b32 v[126:127], v145 offset0:24 offset1:25
	ds_read2st64_b32 v[128:129], v145 offset0:26 offset1:27
	ds_read2st64_b32 v[130:131], v145 offset0:28 offset1:29
	ds_read2st64_b32 v[132:133], v145 offset0:30 offset1:31
	v_sub_u32_e32 v143, s27, v197
	v_ashrrev_i32_e32 v143, 6, v143
	v_lshlrev_b32_e64 v151, v143, -2
	v_not_b32_e32 v151, v151
	v_ashrrev_i32_e32 v144, 31, v143
	v_bfi_b32 v151, v144, 0, v151
	s_waitcnt lgkmcnt(0)
	v_bfe_i32 v134, v151, 0, 1
	v_bfi_b32 v102, v134, v102, v149
	v_bfe_i32 v135, v151, 1, 1
	v_bfi_b32 v103, v135, v103, v149
	v_bfe_i32 v134, v151, 2, 1
	v_bfi_b32 v104, v134, v104, v149
	v_bfe_i32 v135, v151, 3, 1
	v_bfi_b32 v105, v135, v105, v149
	v_bfe_i32 v134, v151, 4, 1
	v_bfi_b32 v106, v134, v106, v149
	v_bfe_i32 v135, v151, 5, 1
	v_bfi_b32 v107, v135, v107, v149
	v_bfe_i32 v134, v151, 6, 1
	v_bfi_b32 v108, v134, v108, v149
	v_bfe_i32 v135, v151, 7, 1
	v_bfi_b32 v109, v135, v109, v149
	v_bfe_i32 v134, v151, 8, 1
	v_bfi_b32 v110, v134, v110, v149
	v_bfe_i32 v135, v151, 9, 1
	v_bfi_b32 v111, v135, v111, v149
	v_bfe_i32 v134, v151, 10, 1
	v_bfi_b32 v112, v134, v112, v149
	v_bfe_i32 v135, v151, 11, 1
	v_bfi_b32 v113, v135, v113, v149
	v_bfe_i32 v134, v151, 12, 1
	v_bfi_b32 v114, v134, v114, v149
	v_bfe_i32 v135, v151, 13, 1
	v_bfi_b32 v115, v135, v115, v149
	v_bfe_i32 v134, v151, 14, 1
	v_bfi_b32 v116, v134, v116, v149
	v_bfe_i32 v135, v151, 15, 1
	v_bfi_b32 v117, v135, v117, v149
	v_bfe_i32 v134, v151, 16, 1
	v_bfi_b32 v118, v134, v118, v149
	v_bfe_i32 v135, v151, 17, 1
	v_bfi_b32 v119, v135, v119, v149
	v_bfe_i32 v134, v151, 18, 1
	v_bfi_b32 v120, v134, v120, v149
	v_bfe_i32 v135, v151, 19, 1
	v_bfi_b32 v121, v135, v121, v149
	v_bfe_i32 v134, v151, 20, 1
	v_bfi_b32 v122, v134, v122, v149
	v_bfe_i32 v135, v151, 21, 1
	v_bfi_b32 v123, v135, v123, v149
	v_bfe_i32 v134, v151, 22, 1
	v_bfi_b32 v124, v134, v124, v149
	v_bfe_i32 v135, v151, 23, 1
	v_bfi_b32 v125, v135, v125, v149
	v_bfe_i32 v134, v151, 24, 1
	v_bfi_b32 v126, v134, v126, v149
	v_bfe_i32 v135, v151, 25, 1
	v_bfi_b32 v127, v135, v127, v149
	v_bfe_i32 v134, v151, 26, 1
	v_bfi_b32 v128, v134, v128, v149
	v_bfe_i32 v135, v151, 27, 1
	v_bfi_b32 v129, v135, v129, v149
	v_bfe_i32 v134, v151, 28, 1
	v_bfi_b32 v130, v134, v130, v149
	v_bfe_i32 v135, v151, 29, 1
	v_bfi_b32 v131, v135, v131, v149
	v_bfe_i32 v134, v151, 30, 1
	v_bfi_b32 v132, v134, v132, v149
	v_bfe_i32 v135, v151, 31, 1
	v_bfi_b32 v133, v135, v133, v149
	s_cmpk_gt_i32 s27, 0xff
	s_cbranch_scc1 .Lsel_search
	s_mov_b32 s0, 0xd1400000
	s_branch .Lsel_mask

.Lsel_nosnap1:
	s_xor_b32 s1, s7, 0x80000000
	s_not_b32 s0, s7
	s_bitcmp1_b32 s7, 31
	s_cselect_b32 s0, s1, s0
	v_mov_b32_e32 v142, s0
	v_mul_f32_e32 v142, s37, v142
	v_fma_f32 v134, v102, s36, v142 clamp
	v_fma_f32 v135, v103, s36, v142 clamp
	v_fma_f32 v136, v104, s36, v142 clamp
	v_fma_f32 v137, v105, s36, v142 clamp
	v_fma_f32 v158, v106, s36, v142 clamp
	v_fma_f32 v159, v107, s36, v142 clamp
	v_fma_f32 v160, v108, s36, v142 clamp
	v_fma_f32 v161, v109, s36, v142 clamp
	v_mfma_f32_16x16x32_bf16 v[138:141], v[154:157], v[134:137], 0
	s_cmp_eq_u32 s46, 1
	s_cbranch_scc1 .Lcnt_red1
	v_fma_f32 v134, v110, s36, v142 clamp
	v_fma_f32 v135, v111, s36, v142 clamp
	v_fma_f32 v136, v112, s36, v142 clamp
	v_fma_f32 v137, v113, s36, v142 clamp
	v_mfma_f32_16x16x32_bf16 v[138:141], v[154:157], v[158:161], v[138:141]
	s_cmp_eq_u32 s46, 2
	s_cbranch_scc1 .Lcnt_red1
	v_fma_f32 v158, v114, s36, v142 clamp
	v_fma_f32 v159, v115, s36, v142 clamp
	v_fma_f32 v160, v116, s36, v142 clamp
	v_fma_f32 v161, v117, s36, v142 clamp
	v_mfma_f32_16x16x32_bf16 v[138:141], v[154:157], v[134:137], v[138:141]
	s_cmp_eq_u32 s46, 3
	s_cbranch_scc1 .Lcnt_red1
	v_fma_f32 v134, v118, s36, v142 clamp
	v_fma_f32 v135, v119, s36, v142 clamp
	v_fma_f32 v136, v120, s36, v142 clamp
	v_fma_f32 v137, v121, s36, v142 clamp
	v_mfma_f32_16x16x32_bf16 v[138:141], v[154:157], v[158:161], v[138:141]
	s_cmp_eq_u32 s46, 4
	s_cbranch_scc1 .Lcnt_red1
	v_fma_f32 v158, v122, s36, v142 clamp
	v_fma_f32 v159, v123, s36, v142 clamp
	v_fma_f32 v160, v124, s36, v142 clamp
	v_fma_f32 v161, v125, s36, v142 clamp
	v_mfma_f32_16x16x32_bf16 v[138:141], v[154:157], v[134:137], v[138:141]
	s_cmp_eq_u32 s46, 5
	s_cbranch_scc1 .Lcnt_red1
	v_fma_f32 v134, v126, s36, v142 clamp
	v_fma_f32 v135, v127, s36, v142 clamp
	v_fma_f32 v136, v128, s36, v142 clamp
	v_fma_f32 v137, v129, s36, v142 clamp
	v_mfma_f32_16x16x32_bf16 v[138:141], v[154:157], v[158:161], v[138:141]
	s_cmp_eq_u32 s46, 6
	s_cbranch_scc1 .Lcnt_red1
	v_fma_f32 v158, v130, s36, v142 clamp
	v_fma_f32 v159, v131, s36, v142 clamp
	v_fma_f32 v160, v132, s36, v142 clamp
	v_fma_f32 v161, v133, s36, v142 clamp
	v_mfma_f32_16x16x32_bf16 v[138:141], v[154:157], v[134:137], v[138:141]
	s_cmp_eq_u32 s46, 7
	s_cbranch_scc1 .Lcnt_red1
	v_mfma_f32_16x16x32_bf16 v[138:141], v[154:157], v[158:161], v[138:141]
.Lcnt_red1:
	s_nop 7
	v_add_f32_dpp v138, v138, v138 quad_perm:[1,0,3,2] row_mask:0xf bank_mask:0xf bound_ctrl:1
	s_nop 1
	v_add_f32_dpp v138, v138, v138 quad_perm:[2,3,0,1] row_mask:0xf bank_mask:0xf bound_ctrl:1
	s_nop 1
	v_add_f32_dpp v138, v138, v138 row_half_mirror row_mask:0xf bank_mask:0xf bound_ctrl:1
	s_nop 1
	v_add_f32_dpp v138, v138, v138 row_mirror row_mask:0xf bank_mask:0xf bound_ctrl:1
	v_cvt_u32_f32_e32 v138, v138
	s_nop 0
	v_readfirstlane_b32 s0, v138
	s_add_i32 s0, s0, s47
	s_sub_i32 s0, 0x800, s0
	s_cmpk_lt_u32 s0, 0x100
	s_cbranch_scc1 .Lsel_bis_hi
	s_mov_b32 s29, s6
	s_mov_b32 s31, s0
	s_cmpk_eq_u32 s0, 0x100
	s_cbranch_scc0 .Lsel_bis
	s_branch .Lsel_bis_done

.Lsel_ties:
	v_mov_b32_e32 v150, s0
	v_mul_f32_e32 v142, s37, v150
	v_fma_f32 v134, v102, s37, -v142 clamp
	v_fma_f32 v135, v103, s37, -v142 clamp
	v_fma_f32 v136, v104, s37, -v142 clamp
	v_fma_f32 v137, v105, s37, -v142 clamp
	v_fma_f32 v158, v106, s37, -v142 clamp
	v_fma_f32 v159, v107, s37, -v142 clamp
	v_fma_f32 v160, v108, s37, -v142 clamp
	v_fma_f32 v161, v109, s37, -v142 clamp
	v_mfma_f32_16x16x32_bf16 v[138:141], v[154:157], v[134:137], 0
	s_cmp_eq_u32 s46, 1
	s_cbranch_scc1 .Lcnt_red2
	v_fma_f32 v134, v110, s37, -v142 clamp
	v_fma_f32 v135, v111, s37, -v142 clamp
	v_fma_f32 v136, v112, s37, -v142 clamp
	v_fma_f32 v137, v113, s37, -v142 clamp
	v_mfma_f32_16x16x32_bf16 v[138:141], v[154:157], v[158:161], v[138:141]
	s_cmp_eq_u32 s46, 2
	s_cbranch_scc1 .Lcnt_red2
	v_fma_f32 v158, v114, s37, -v142 clamp
	v_fma_f32 v159, v115, s37, -v142 clamp
	v_fma_f32 v160, v116, s37, -v142 clamp
	v_fma_f32 v161, v117, s37, -v142 clamp
	v_mfma_f32_16x16x32_bf16 v[138:141], v[154:157], v[134:137], v[138:141]
	s_cmp_eq_u32 s46, 3
	s_cbranch_scc1 .Lcnt_red2
	v_fma_f32 v134, v118, s37, -v142 clamp
	v_fma_f32 v135, v119, s37, -v142 clamp
	v_fma_f32 v136, v120, s37, -v142 clamp
	v_fma_f32 v137, v121, s37, -v142 clamp
	v_mfma_f32_16x16x32_bf16 v[138:141], v[154:157], v[158:161], v[138:141]
	s_cmp_eq_u32 s46, 4
	s_cbranch_scc1 .Lcnt_red2
	v_fma_f32 v158, v122, s37, -v142 clamp
	v_fma_f32 v159, v123, s37, -v142 clamp
	v_fma_f32 v160, v124, s37, -v142 clamp
	v_fma_f32 v161, v125, s37, -v142 clamp
	v_mfma_f32_16x16x32_bf16 v[138:141], v[154:157], v[134:137], v[138:141]
	s_cmp_eq_u32 s46, 5
	s_cbranch_scc1 .Lcnt_red2
	v_fma_f32 v134, v126, s37, -v142 clamp
	v_fma_f32 v135, v127, s37, -v142 clamp
	v_fma_f32 v136, v128, s37, -v142 clamp
	v_fma_f32 v137, v129, s37, -v142 clamp
	v_mfma_f32_16x16x32_bf16 v[138:141], v[154:157], v[158:161], v[138:141]
	s_cmp_eq_u32 s46, 6
	s_cbranch_scc1 .Lcnt_red2
	v_fma_f32 v158, v130, s37, -v142 clamp
	v_fma_f32 v159, v131, s37, -v142 clamp
	v_fma_f32 v160, v132, s37, -v142 clamp
	v_fma_f32 v161, v133, s37, -v142 clamp
	v_mfma_f32_16x16x32_bf16 v[138:141], v[154:157], v[134:137], v[138:141]
	s_cmp_eq_u32 s46, 7
	s_cbranch_scc1 .Lcnt_red2
	v_mfma_f32_16x16x32_bf16 v[138:141], v[154:157], v[158:161], v[138:141]
.Lcnt_red2:
	s_nop 7
	v_add_f32_dpp v138, v138, v138 quad_perm:[1,0,3,2] row_mask:0xf bank_mask:0xf bound_ctrl:1
	s_nop 1
	v_add_f32_dpp v138, v138, v138 quad_perm:[2,3,0,1] row_mask:0xf bank_mask:0xf bound_ctrl:1
	s_nop 1
	v_add_f32_dpp v138, v138, v138 row_half_mirror row_mask:0xf bank_mask:0xf bound_ctrl:1
	s_nop 1
	v_add_f32_dpp v138, v138, v138 row_mirror row_mask:0xf bank_mask:0xf bound_ctrl:1
	v_cvt_u32_f32_e32 v138, v138
	s_nop 0
	v_readfirstlane_b32 s0, v138
	s_sub_i32 s38, 0x100, s0
	s_mov_b32 s39, 0
	v_mov_b32_e32 v146, 0
	v_cmp_eq_f32_e64 s[42:43], v102, v150
	v_fma_f32 v134, v102, s37, -v142 clamp
	v_cvt_u32_f32_e32 v134, v134
	v_mbcnt_lo_u32_b32 v135, s42, 0
	v_mbcnt_hi_u32_b32 v135, s43, v135
	v_add_u32_e32 v135, s39, v135
	v_cmp_gt_u32_e32 vcc, s38, v135
	s_nop 1
	s_and_b64 vcc, vcc, s[42:43]
	s_nop 1
	v_cndmask_b32_e64 v136, 0, 1, vcc
	v_or_b32_e32 v136, v136, v134
	v_lshl_or_b32 v146, v136, 0, v146
	s_bcnt1_i32_b64 s0, s[42:43]
	s_add_i32 s39, s39, s0
	v_cmp_eq_f32_e64 s[42:43], v103, v150
	v_fma_f32 v134, v103, s37, -v142 clamp
	v_cvt_u32_f32_e32 v134, v134
	v_mbcnt_lo_u32_b32 v135, s42, 0
	v_mbcnt_hi_u32_b32 v135, s43, v135
	v_add_u32_e32 v135, s39, v135
	v_cmp_gt_u32_e32 vcc, s38, v135
	s_nop 1
	s_and_b64 vcc, vcc, s[42:43]
	s_nop 1
	v_cndmask_b32_e64 v136, 0, 1, vcc
	v_or_b32_e32 v136, v136, v134
	v_lshl_or_b32 v146, v136, 1, v146
	s_bcnt1_i32_b64 s0, s[42:43]
	s_add_i32 s39, s39, s0
	v_cmp_eq_f32_e64 s[42:43], v104, v150
	v_fma_f32 v134, v104, s37, -v142 clamp
	v_cvt_u32_f32_e32 v134, v134
	v_mbcnt_lo_u32_b32 v135, s42, 0
	v_mbcnt_hi_u32_b32 v135, s43, v135
	v_add_u32_e32 v135, s39, v135
	v_cmp_gt_u32_e32 vcc, s38, v135
	s_nop 1
	s_and_b64 vcc, vcc, s[42:43]
	s_nop 1
	v_cndmask_b32_e64 v136, 0, 1, vcc
	v_or_b32_e32 v136, v136, v134
	v_lshl_or_b32 v146, v136, 2, v146
	s_bcnt1_i32_b64 s0, s[42:43]
	s_add_i32 s39, s39, s0
	v_cmp_eq_f32_e64 s[42:43], v105, v150
	v_fma_f32 v134, v105, s37, -v142 clamp
	v_cvt_u32_f32_e32 v134, v134
	v_mbcnt_lo_u32_b32 v135, s42, 0
	v_mbcnt_hi_u32_b32 v135, s43, v135
	v_add_u32_e32 v135, s39, v135
	v_cmp_gt_u32_e32 vcc, s38, v135
	s_nop 1
	s_and_b64 vcc, vcc, s[42:43]
	s_nop 1
	v_cndmask_b32_e64 v136, 0, 1, vcc
	v_or_b32_e32 v136, v136, v134
	v_lshl_or_b32 v146, v136, 3, v146
	s_bcnt1_i32_b64 s0, s[42:43]
	s_add_i32 s39, s39, s0
	v_cmp_eq_f32_e64 s[42:43], v106, v150
	v_fma_f32 v134, v106, s37, -v142 clamp
	v_cvt_u32_f32_e32 v134, v134
	v_mbcnt_lo_u32_b32 v135, s42, 0
	v_mbcnt_hi_u32_b32 v135, s43, v135
	v_add_u32_e32 v135, s39, v135
	v_cmp_gt_u32_e32 vcc, s38, v135
	s_nop 1
	s_and_b64 vcc, vcc, s[42:43]
	s_nop 1
	v_cndmask_b32_e64 v136, 0, 1, vcc
	v_or_b32_e32 v136, v136, v134
	v_lshl_or_b32 v146, v136, 4, v146
	s_bcnt1_i32_b64 s0, s[42:43]
	s_add_i32 s39, s39, s0
	v_cmp_eq_f32_e64 s[42:43], v107, v150
	v_fma_f32 v134, v107, s37, -v142 clamp
	v_cvt_u32_f32_e32 v134, v134
	v_mbcnt_lo_u32_b32 v135, s42, 0
	v_mbcnt_hi_u32_b32 v135, s43, v135
	v_add_u32_e32 v135, s39, v135
	v_cmp_gt_u32_e32 vcc, s38, v135
	s_nop 1
	s_and_b64 vcc, vcc, s[42:43]
	s_nop 1
	v_cndmask_b32_e64 v136, 0, 1, vcc
	v_or_b32_e32 v136, v136, v134
	v_lshl_or_b32 v146, v136, 5, v146
	s_bcnt1_i32_b64 s0, s[42:43]
	s_add_i32 s39, s39, s0
	v_cmp_eq_f32_e64 s[42:43], v108, v150
	v_fma_f32 v134, v108, s37, -v142 clamp
	v_cvt_u32_f32_e32 v134, v134
	v_mbcnt_lo_u32_b32 v135, s42, 0
	v_mbcnt_hi_u32_b32 v135, s43, v135
	v_add_u32_e32 v135, s39, v135
	v_cmp_gt_u32_e32 vcc, s38, v135
	s_nop 1
	s_and_b64 vcc, vcc, s[42:43]
	s_nop 1
	v_cndmask_b32_e64 v136, 0, 1, vcc
	v_or_b32_e32 v136, v136, v134
	v_lshl_or_b32 v146, v136, 6, v146
	s_bcnt1_i32_b64 s0, s[42:43]
	s_add_i32 s39, s39, s0
	v_cmp_eq_f32_e64 s[42:43], v109, v150
	v_fma_f32 v134, v109, s37, -v142 clamp
	v_cvt_u32_f32_e32 v134, v134
	v_mbcnt_lo_u32_b32 v135, s42, 0
	v_mbcnt_hi_u32_b32 v135, s43, v135
	v_add_u32_e32 v135, s39, v135
	v_cmp_gt_u32_e32 vcc, s38, v135
	s_nop 1
	s_and_b64 vcc, vcc, s[42:43]
	s_nop 1
	v_cndmask_b32_e64 v136, 0, 1, vcc
	v_or_b32_e32 v136, v136, v134
	v_lshl_or_b32 v146, v136, 7, v146
	s_bcnt1_i32_b64 s0, s[42:43]
	s_add_i32 s39, s39, s0
	v_cmp_eq_f32_e64 s[42:43], v110, v150
	v_fma_f32 v134, v110, s37, -v142 clamp
	v_cvt_u32_f32_e32 v134, v134
	v_mbcnt_lo_u32_b32 v135, s42, 0
	v_mbcnt_hi_u32_b32 v135, s43, v135
	v_add_u32_e32 v135, s39, v135
	v_cmp_gt_u32_e32 vcc, s38, v135
	s_nop 1
	s_and_b64 vcc, vcc, s[42:43]
	s_nop 1
	v_cndmask_b32_e64 v136, 0, 1, vcc
	v_or_b32_e32 v136, v136, v134
	v_lshl_or_b32 v146, v136, 8, v146
	s_bcnt1_i32_b64 s0, s[42:43]
	s_add_i32 s39, s39, s0
	v_cmp_eq_f32_e64 s[42:43], v111, v150
	v_fma_f32 v134, v111, s37, -v142 clamp
	v_cvt_u32_f32_e32 v134, v134
	v_mbcnt_lo_u32_b32 v135, s42, 0
	v_mbcnt_hi_u32_b32 v135, s43, v135
	v_add_u32_e32 v135, s39, v135
	v_cmp_gt_u32_e32 vcc, s38, v135
	s_nop 1
	s_and_b64 vcc, vcc, s[42:43]
	s_nop 1
	v_cndmask_b32_e64 v136, 0, 1, vcc
	v_or_b32_e32 v136, v136, v134
	v_lshl_or_b32 v146, v136, 9, v146
	s_bcnt1_i32_b64 s0, s[42:43]
	s_add_i32 s39, s39, s0
	v_cmp_eq_f32_e64 s[42:43], v112, v150
	v_fma_f32 v134, v112, s37, -v142 clamp
	v_cvt_u32_f32_e32 v134, v134
	v_mbcnt_lo_u32_b32 v135, s42, 0
	v_mbcnt_hi_u32_b32 v135, s43, v135
	v_add_u32_e32 v135, s39, v135
	v_cmp_gt_u32_e32 vcc, s38, v135
	s_nop 1
	s_and_b64 vcc, vcc, s[42:43]
	s_nop 1
	v_cndmask_b32_e64 v136, 0, 1, vcc
	v_or_b32_e32 v136, v136, v134
	v_lshl_or_b32 v146, v136, 10, v146
	s_bcnt1_i32_b64 s0, s[42:43]
	s_add_i32 s39, s39, s0
	v_cmp_eq_f32_e64 s[42:43], v113, v150
	v_fma_f32 v134, v113, s37, -v142 clamp
	v_cvt_u32_f32_e32 v134, v134
	v_mbcnt_lo_u32_b32 v135, s42, 0
	v_mbcnt_hi_u32_b32 v135, s43, v135
	v_add_u32_e32 v135, s39, v135
	v_cmp_gt_u32_e32 vcc, s38, v135
	s_nop 1
	s_and_b64 vcc, vcc, s[42:43]
	s_nop 1
	v_cndmask_b32_e64 v136, 0, 1, vcc
	v_or_b32_e32 v136, v136, v134
	v_lshl_or_b32 v146, v136, 11, v146
	s_bcnt1_i32_b64 s0, s[42:43]
	s_add_i32 s39, s39, s0
	v_cmp_eq_f32_e64 s[42:43], v114, v150
	v_fma_f32 v134, v114, s37, -v142 clamp
	v_cvt_u32_f32_e32 v134, v134
	v_mbcnt_lo_u32_b32 v135, s42, 0
	v_mbcnt_hi_u32_b32 v135, s43, v135
	v_add_u32_e32 v135, s39, v135
	v_cmp_gt_u32_e32 vcc, s38, v135
	s_nop 1
	s_and_b64 vcc, vcc, s[42:43]
	s_nop 1
	v_cndmask_b32_e64 v136, 0, 1, vcc
	v_or_b32_e32 v136, v136, v134
	v_lshl_or_b32 v146, v136, 12, v146
	s_bcnt1_i32_b64 s0, s[42:43]
	s_add_i32 s39, s39, s0
	v_cmp_eq_f32_e64 s[42:43], v115, v150
	v_fma_f32 v134, v115, s37, -v142 clamp
	v_cvt_u32_f32_e32 v134, v134
	v_mbcnt_lo_u32_b32 v135, s42, 0
	v_mbcnt_hi_u32_b32 v135, s43, v135
	v_add_u32_e32 v135, s39, v135
	v_cmp_gt_u32_e32 vcc, s38, v135
	s_nop 1
	s_and_b64 vcc, vcc, s[42:43]
	s_nop 1
	v_cndmask_b32_e64 v136, 0, 1, vcc
	v_or_b32_e32 v136, v136, v134
	v_lshl_or_b32 v146, v136, 13, v146
	s_bcnt1_i32_b64 s0, s[42:43]
	s_add_i32 s39, s39, s0
	v_cmp_eq_f32_e64 s[42:43], v116, v150
	v_fma_f32 v134, v116, s37, -v142 clamp
	v_cvt_u32_f32_e32 v134, v134
	v_mbcnt_lo_u32_b32 v135, s42, 0
	v_mbcnt_hi_u32_b32 v135, s43, v135
	v_add_u32_e32 v135, s39, v135
	v_cmp_gt_u32_e32 vcc, s38, v135
	s_nop 1
	s_and_b64 vcc, vcc, s[42:43]
	s_nop 1
	v_cndmask_b32_e64 v136, 0, 1, vcc
	v_or_b32_e32 v136, v136, v134
	v_lshl_or_b32 v146, v136, 14, v146
	s_bcnt1_i32_b64 s0, s[42:43]
	s_add_i32 s39, s39, s0
	v_cmp_eq_f32_e64 s[42:43], v117, v150
	v_fma_f32 v134, v117, s37, -v142 clamp
	v_cvt_u32_f32_e32 v134, v134
	v_mbcnt_lo_u32_b32 v135, s42, 0
	v_mbcnt_hi_u32_b32 v135, s43, v135
	v_add_u32_e32 v135, s39, v135
	v_cmp_gt_u32_e32 vcc, s38, v135
	s_nop 1
	s_and_b64 vcc, vcc, s[42:43]
	s_nop 1
	v_cndmask_b32_e64 v136, 0, 1, vcc
	v_or_b32_e32 v136, v136, v134
	v_lshl_or_b32 v146, v136, 15, v146
	s_bcnt1_i32_b64 s0, s[42:43]
	s_add_i32 s39, s39, s0
	v_cmp_eq_f32_e64 s[42:43], v118, v150
	v_fma_f32 v134, v118, s37, -v142 clamp
	v_cvt_u32_f32_e32 v134, v134
	v_mbcnt_lo_u32_b32 v135, s42, 0
	v_mbcnt_hi_u32_b32 v135, s43, v135
	v_add_u32_e32 v135, s39, v135
	v_cmp_gt_u32_e32 vcc, s38, v135
	s_nop 1
	s_and_b64 vcc, vcc, s[42:43]
	s_nop 1
	v_cndmask_b32_e64 v136, 0, 1, vcc
	v_or_b32_e32 v136, v136, v134
	v_lshl_or_b32 v146, v136, 16, v146
	s_bcnt1_i32_b64 s0, s[42:43]
	s_add_i32 s39, s39, s0
	v_cmp_eq_f32_e64 s[42:43], v119, v150
	v_fma_f32 v134, v119, s37, -v142 clamp
	v_cvt_u32_f32_e32 v134, v134
	v_mbcnt_lo_u32_b32 v135, s42, 0
	v_mbcnt_hi_u32_b32 v135, s43, v135
	v_add_u32_e32 v135, s39, v135
	v_cmp_gt_u32_e32 vcc, s38, v135
	s_nop 1
	s_and_b64 vcc, vcc, s[42:43]
	s_nop 1
	v_cndmask_b32_e64 v136, 0, 1, vcc
	v_or_b32_e32 v136, v136, v134
	v_lshl_or_b32 v146, v136, 17, v146
	s_bcnt1_i32_b64 s0, s[42:43]
	s_add_i32 s39, s39, s0
	v_cmp_eq_f32_e64 s[42:43], v120, v150
	v_fma_f32 v134, v120, s37, -v142 clamp
	v_cvt_u32_f32_e32 v134, v134
	v_mbcnt_lo_u32_b32 v135, s42, 0
	v_mbcnt_hi_u32_b32 v135, s43, v135
	v_add_u32_e32 v135, s39, v135
	v_cmp_gt_u32_e32 vcc, s38, v135
	s_nop 1
	s_and_b64 vcc, vcc, s[42:43]
	s_nop 1
	v_cndmask_b32_e64 v136, 0, 1, vcc
	v_or_b32_e32 v136, v136, v134
	v_lshl_or_b32 v146, v136, 18, v146
	s_bcnt1_i32_b64 s0, s[42:43]
	s_add_i32 s39, s39, s0
	v_cmp_eq_f32_e64 s[42:43], v121, v150
	v_fma_f32 v134, v121, s37, -v142 clamp
	v_cvt_u32_f32_e32 v134, v134
	v_mbcnt_lo_u32_b32 v135, s42, 0
	v_mbcnt_hi_u32_b32 v135, s43, v135
	v_add_u32_e32 v135, s39, v135
	v_cmp_gt_u32_e32 vcc, s38, v135
	s_nop 1
	s_and_b64 vcc, vcc, s[42:43]
	s_nop 1
	v_cndmask_b32_e64 v136, 0, 1, vcc
	v_or_b32_e32 v136, v136, v134
	v_lshl_or_b32 v146, v136, 19, v146
	s_bcnt1_i32_b64 s0, s[42:43]
	s_add_i32 s39, s39, s0
	v_cmp_eq_f32_e64 s[42:43], v122, v150
	v_fma_f32 v134, v122, s37, -v142 clamp
	v_cvt_u32_f32_e32 v134, v134
	v_mbcnt_lo_u32_b32 v135, s42, 0
	v_mbcnt_hi_u32_b32 v135, s43, v135
	v_add_u32_e32 v135, s39, v135
	v_cmp_gt_u32_e32 vcc, s38, v135
	s_nop 1
	s_and_b64 vcc, vcc, s[42:43]
	s_nop 1
	v_cndmask_b32_e64 v136, 0, 1, vcc
	v_or_b32_e32 v136, v136, v134
	v_lshl_or_b32 v146, v136, 20, v146
	s_bcnt1_i32_b64 s0, s[42:43]
	s_add_i32 s39, s39, s0
	v_cmp_eq_f32_e64 s[42:43], v123, v150
	v_fma_f32 v134, v123, s37, -v142 clamp
	v_cvt_u32_f32_e32 v134, v134
	v_mbcnt_lo_u32_b32 v135, s42, 0
	v_mbcnt_hi_u32_b32 v135, s43, v135
	v_add_u32_e32 v135, s39, v135
	v_cmp_gt_u32_e32 vcc, s38, v135
	s_nop 1
	s_and_b64 vcc, vcc, s[42:43]
	s_nop 1
	v_cndmask_b32_e64 v136, 0, 1, vcc
	v_or_b32_e32 v136, v136, v134
	v_lshl_or_b32 v146, v136, 21, v146
	s_bcnt1_i32_b64 s0, s[42:43]
	s_add_i32 s39, s39, s0
	v_cmp_eq_f32_e64 s[42:43], v124, v150
	v_fma_f32 v134, v124, s37, -v142 clamp
	v_cvt_u32_f32_e32 v134, v134
	v_mbcnt_lo_u32_b32 v135, s42, 0
	v_mbcnt_hi_u32_b32 v135, s43, v135
	v_add_u32_e32 v135, s39, v135
	v_cmp_gt_u32_e32 vcc, s38, v135
	s_nop 1
	s_and_b64 vcc, vcc, s[42:43]
	s_nop 1
	v_cndmask_b32_e64 v136, 0, 1, vcc
	v_or_b32_e32 v136, v136, v134
	v_lshl_or_b32 v146, v136, 22, v146
	s_bcnt1_i32_b64 s0, s[42:43]
	s_add_i32 s39, s39, s0
	v_cmp_eq_f32_e64 s[42:43], v125, v150
	v_fma_f32 v134, v125, s37, -v142 clamp
	v_cvt_u32_f32_e32 v134, v134
	v_mbcnt_lo_u32_b32 v135, s42, 0
	v_mbcnt_hi_u32_b32 v135, s43, v135
	v_add_u32_e32 v135, s39, v135
	v_cmp_gt_u32_e32 vcc, s38, v135
	s_nop 1
	s_and_b64 vcc, vcc, s[42:43]
	s_nop 1
	v_cndmask_b32_e64 v136, 0, 1, vcc
	v_or_b32_e32 v136, v136, v134
	v_lshl_or_b32 v146, v136, 23, v146
	s_bcnt1_i32_b64 s0, s[42:43]
	s_add_i32 s39, s39, s0
	v_cmp_eq_f32_e64 s[42:43], v126, v150
	v_fma_f32 v134, v126, s37, -v142 clamp
	v_cvt_u32_f32_e32 v134, v134
	v_mbcnt_lo_u32_b32 v135, s42, 0
	v_mbcnt_hi_u32_b32 v135, s43, v135
	v_add_u32_e32 v135, s39, v135
	v_cmp_gt_u32_e32 vcc, s38, v135
	s_nop 1
	s_and_b64 vcc, vcc, s[42:43]
	s_nop 1
	v_cndmask_b32_e64 v136, 0, 1, vcc
	v_or_b32_e32 v136, v136, v134
	v_lshl_or_b32 v146, v136, 24, v146
	s_bcnt1_i32_b64 s0, s[42:43]
	s_add_i32 s39, s39, s0
	v_cmp_eq_f32_e64 s[42:43], v127, v150
	v_fma_f32 v134, v127, s37, -v142 clamp
	v_cvt_u32_f32_e32 v134, v134
	v_mbcnt_lo_u32_b32 v135, s42, 0
	v_mbcnt_hi_u32_b32 v135, s43, v135
	v_add_u32_e32 v135, s39, v135
	v_cmp_gt_u32_e32 vcc, s38, v135
	s_nop 1
	s_and_b64 vcc, vcc, s[42:43]
	s_nop 1
	v_cndmask_b32_e64 v136, 0, 1, vcc
	v_or_b32_e32 v136, v136, v134
	v_lshl_or_b32 v146, v136, 25, v146
	s_bcnt1_i32_b64 s0, s[42:43]
	s_add_i32 s39, s39, s0
	v_cmp_eq_f32_e64 s[42:43], v128, v150
	v_fma_f32 v134, v128, s37, -v142 clamp
	v_cvt_u32_f32_e32 v134, v134
	v_mbcnt_lo_u32_b32 v135, s42, 0
	v_mbcnt_hi_u32_b32 v135, s43, v135
	v_add_u32_e32 v135, s39, v135
	v_cmp_gt_u32_e32 vcc, s38, v135
	s_nop 1
	s_and_b64 vcc, vcc, s[42:43]
	s_nop 1
	v_cndmask_b32_e64 v136, 0, 1, vcc
	v_or_b32_e32 v136, v136, v134
	v_lshl_or_b32 v146, v136, 26, v146
	s_bcnt1_i32_b64 s0, s[42:43]
	s_add_i32 s39, s39, s0
	v_cmp_eq_f32_e64 s[42:43], v129, v150
	v_fma_f32 v134, v129, s37, -v142 clamp
	v_cvt_u32_f32_e32 v134, v134
	v_mbcnt_lo_u32_b32 v135, s42, 0
	v_mbcnt_hi_u32_b32 v135, s43, v135
	v_add_u32_e32 v135, s39, v135
	v_cmp_gt_u32_e32 vcc, s38, v135
	s_nop 1
	s_and_b64 vcc, vcc, s[42:43]
	s_nop 1
	v_cndmask_b32_e64 v136, 0, 1, vcc
	v_or_b32_e32 v136, v136, v134
	v_lshl_or_b32 v146, v136, 27, v146
	s_bcnt1_i32_b64 s0, s[42:43]
	s_add_i32 s39, s39, s0
	v_cmp_eq_f32_e64 s[42:43], v130, v150
	v_fma_f32 v134, v130, s37, -v142 clamp
	v_cvt_u32_f32_e32 v134, v134
	v_mbcnt_lo_u32_b32 v135, s42, 0
	v_mbcnt_hi_u32_b32 v135, s43, v135
	v_add_u32_e32 v135, s39, v135
	v_cmp_gt_u32_e32 vcc, s38, v135
	s_nop 1
	s_and_b64 vcc, vcc, s[42:43]
	s_nop 1
	v_cndmask_b32_e64 v136, 0, 1, vcc
	v_or_b32_e32 v136, v136, v134
	v_lshl_or_b32 v146, v136, 28, v146
	s_bcnt1_i32_b64 s0, s[42:43]
	s_add_i32 s39, s39, s0
	v_cmp_eq_f32_e64 s[42:43], v131, v150
	v_fma_f32 v134, v131, s37, -v142 clamp
	v_cvt_u32_f32_e32 v134, v134
	v_mbcnt_lo_u32_b32 v135, s42, 0
	v_mbcnt_hi_u32_b32 v135, s43, v135
	v_add_u32_e32 v135, s39, v135
	v_cmp_gt_u32_e32 vcc, s38, v135
	s_nop 1
	s_and_b64 vcc, vcc, s[42:43]
	s_nop 1
	v_cndmask_b32_e64 v136, 0, 1, vcc
	v_or_b32_e32 v136, v136, v134
	v_lshl_or_b32 v146, v136, 29, v146
	s_bcnt1_i32_b64 s0, s[42:43]
	s_add_i32 s39, s39, s0
	v_cmp_eq_f32_e64 s[42:43], v132, v150
	v_fma_f32 v134, v132, s37, -v142 clamp
	v_cvt_u32_f32_e32 v134, v134
	v_mbcnt_lo_u32_b32 v135, s42, 0
	v_mbcnt_hi_u32_b32 v135, s43, v135
	v_add_u32_e32 v135, s39, v135
	v_cmp_gt_u32_e32 vcc, s38, v135
	s_nop 1
	s_and_b64 vcc, vcc, s[42:43]
	s_nop 1
	v_cndmask_b32_e64 v136, 0, 1, vcc
	v_or_b32_e32 v136, v136, v134
	v_lshl_or_b32 v146, v136, 30, v146
	s_bcnt1_i32_b64 s0, s[42:43]
	s_add_i32 s39, s39, s0
	v_cmp_eq_f32_e64 s[42:43], v133, v150
	v_fma_f32 v134, v133, s37, -v142 clamp
	v_cvt_u32_f32_e32 v134, v134
	v_mbcnt_lo_u32_b32 v135, s42, 0
	v_mbcnt_hi_u32_b32 v135, s43, v135
	v_add_u32_e32 v135, s39, v135
	v_cmp_gt_u32_e32 vcc, s38, v135
	s_nop 1
	s_and_b64 vcc, vcc, s[42:43]
	s_nop 1
	v_cndmask_b32_e64 v136, 0, 1, vcc
	v_or_b32_e32 v136, v136, v134
	v_lshl_or_b32 v146, v136, 31, v146
	s_bcnt1_i32_b64 s0, s[42:43]
	s_add_i32 s39, s39, s0
	s_branch .Lsel_store
